# Q GEMM and layer-1 in_proj epilogues: row statistics loaded once per lane and shared via ds_bpermute (as MLP1)
# speedup vs baseline: 1.0029x; 1.0029x over previous
.LBB0_381:
	s_lshl_b32 s1, s2, 8
	s_lshl_b32 s0, s0, 8
	v_mov_b32_e32 v72, v210
	v_mov_b32_e32 v160, v179
	s_add_i32 s1, s1, s72
	s_or_b32 s0, s0, s73
	s_nop 0
	v_lshl_add_u32 v196, v72, 3, s0
	v_add_u32_e32 v200, s1, v160
	v_ashrrev_i32_e32 v197, 31, v196
	v_ashrrev_i32_e32 v201, 31, v200
	v_lshlrev_b64 v[72:73], 2, v[196:197]
	v_lshl_add_u64 v[74:75], s[52:53], 0, v[72:73]
	v_lshl_add_u64 v[84:85], s[56:57], 0, v[72:73]
	global_load_dwordx4 v[100:103], v[74:75], off offset:16
	global_load_dwordx4 v[108:111], v[74:75], off
	global_load_dwordx4 v[96:99], v[84:85], off offset:16
	global_load_dwordx4 v[104:107], v[84:85], off
	global_load_dwordx4 v[76:79], v[74:75], off offset:528
	global_load_dwordx4 v[88:91], v[74:75], off offset:512
	s_nop 0
	global_load_dwordx4 v[72:75], v[84:85], off offset:528
	s_nop 0
	global_load_dwordx4 v[84:87], v[84:85], off offset:512
	s_nop 0
	v_lshl_add_u32 v170, v210, 4, v200
	v_lshlrev_b32_e32 v170, 5, v170
	v_add_u32_e32 v232, 0x1000, v170
	global_load_dwordx4 v[160:163], v170, s[54:55] offset:16
	global_load_dwordx4 v[164:167], v170, s[54:55]
	global_load_dwordx4 v[214:217], v232, s[54:55] offset:16
	global_load_dwordx4 v[218:221], v232, s[54:55]
	v_lshlrev_b32_e32 v234, 2, v179
	s_mov_b32 s0, 0x3a800000
	s_mov_b32 s1, 0x800000
	v_add_u32_e32 v202, 16, v200
	v_ashrrev_i32_e32 v203, 31, v202
	v_lshlrev_b64 v[198:199], 11, v[200:201]
	v_lshl_add_u64 v[198:199], s[24:25], 0, v[198:199]
	v_lshl_add_u64 v[208:209], v[196:197], 1, v[198:199]
	s_waitcnt vmcnt(0)
	v_pk_add_f32 v[160:161], v[160:161], v[162:163]
	v_pk_add_f32 v[164:165], v[164:165], v[166:167]
	v_pk_add_f32 v[160:161], v[164:165], v[160:161]
	v_pk_mul_f32 v[160:161], v[160:161], s[0:1] op_sel_hi:[1,0]
	s_nop 0
	v_fma_f32 v164, -v160, v160, v161
	v_max_f32_e32 v164, 0, v164
	v_add_f32_e32 v164, 0x3727c5ac, v164
	v_cmp_gt_f32_e32 vcc, s1, v164
	v_mul_f32_e32 v165, 0x4b800000, v164
	v_mov_b32_e32 v222, v160
	v_cndmask_b32_e32 v164, v164, v165, vcc
	v_rsq_f32_e32 v164, v164
	s_nop 0
	v_mul_f32_e32 v165, 0x45800000, v164
	v_cndmask_b32_e32 v223, v164, v165, vcc
	v_pk_add_f32 v[214:215], v[214:215], v[216:217]
	v_pk_add_f32 v[218:219], v[218:219], v[220:221]
	v_pk_add_f32 v[214:215], v[218:219], v[214:215]
	v_pk_mul_f32 v[214:215], v[214:215], s[0:1] op_sel_hi:[1,0]
	s_nop 0
	v_fma_f32 v218, -v214, v214, v215
	v_max_f32_e32 v218, 0, v218
	v_add_f32_e32 v218, 0x3727c5ac, v218
	v_cmp_gt_f32_e32 vcc, s1, v218
	v_mul_f32_e32 v219, 0x4b800000, v218
	v_mov_b32_e32 v213, v214
	v_cndmask_b32_e32 v218, v218, v219, vcc
	v_rsq_f32_e32 v218, v218
	s_nop 0
	v_mul_f32_e32 v219, 0x45800000, v218
	v_cndmask_b32_e32 v241, v218, v219, vcc
	ds_bpermute_b32 v174, v234, v222
	ds_bpermute_b32 v175, v234, v223
	ds_bpermute_b32 v176, v234, v222 offset:64
	ds_bpermute_b32 v177, v234, v223 offset:64
	v_xor_b32_e32 v103, 0x80000000, v103
	v_xor_b32_e32 v199, 0x80000000, v111
	v_xor_b32_e32 v198, 0x80000000, v110
	v_xor_b32_e32 v102, 0x80000000, v102
	s_waitcnt lgkmcnt(2)
	v_mov_b32_e32 v204, v174
	v_mov_b32_e32 v206, v175
	v_mov_b32_e32 v205, v204
	v_mov_b32_e32 v207, v206
	v_cmp_gt_i32_e32 vcc, 2.0, v196
	s_and_saveexec_b64 s[0:1], vcc
	s_cbranch_execz .LBB0_383
	v_pk_fma_f32 v[156:157], v[108:109], v[204:205], v[156:157] neg_lo:[1,0,0] neg_hi:[1,0,0]
	s_mov_b32 s2, 0x3d800000
	v_pk_fma_f32 v[156:157], v[156:157], v[206:207], v[104:105]
	v_pk_mul_f32 v[156:157], v[156:157], s[2:3] op_sel_hi:[1,0]
	v_pk_fma_f32 v[158:159], v[198:199], v[204:205], v[158:159]
	v_pk_fma_f32 v[152:153], v[100:101], v[204:205], v[152:153] neg_lo:[1,0,0] neg_hi:[1,0,0]
	v_pk_fma_f32 v[158:159], v[158:159], v[206:207], v[106:107]
	v_pk_fma_f32 v[152:153], v[152:153], v[206:207], v[96:97]
	v_pk_mul_f32 v[158:159], v[158:159], s[2:3] op_sel_hi:[1,0]
	v_pk_mul_f32 v[152:153], v[152:153], s[2:3] op_sel_hi:[1,0]
	v_cvt_pk_bf16_f32 v156, v156, v157
	v_pk_fma_f32 v[110:111], v[102:103], v[204:205], v[154:155]
	v_pk_fma_f32 v[110:111], v[110:111], v[206:207], v[98:99]
	v_pk_mul_f32 v[110:111], v[110:111], s[2:3] op_sel_hi:[1,0]
	v_cvt_pk_bf16_f32 v157, v158, v159
	v_cvt_pk_bf16_f32 v158, v152, v153
	v_cvt_pk_bf16_f32 v159, v110, v111
	global_store_dwordx4 v[208:209], v[156:159], off

.LBB0_385:
	s_or_b64 exec, exec, s[0:1]
	s_waitcnt lgkmcnt(0)
	v_mov_b32_e32 v152, v176
	v_mov_b32_e32 v154, v177
	ds_bpermute_b32 v174, v234, v222 offset:128
	ds_bpermute_b32 v175, v234, v223 offset:128
	v_lshlrev_b64 v[156:157], 11, v[202:203]
	v_lshl_add_u64 v[156:157], s[24:25], 0, v[156:157]
	v_lshl_add_u64 v[156:157], v[196:197], 1, v[156:157]
	v_mov_b32_e32 v153, v152
	v_add_u32_e32 v110, 32, v200
	v_ashrrev_i32_e32 v111, 31, v110
	v_mov_b32_e32 v155, v154
	s_and_saveexec_b64 s[0:1], vcc
	s_cbranch_execz .LBB0_387
	v_pk_fma_f32 v[140:141], v[108:109], v[152:153], v[140:141] neg_lo:[1,0,0] neg_hi:[1,0,0]
	s_mov_b32 s2, 0x3d800000
	v_pk_fma_f32 v[140:141], v[140:141], v[154:155], v[104:105]
	v_pk_mul_f32 v[140:141], v[140:141], s[2:3] op_sel_hi:[1,0]
	v_pk_fma_f32 v[142:143], v[198:199], v[152:153], v[142:143]
	v_pk_fma_f32 v[142:143], v[142:143], v[154:155], v[106:107]
	v_pk_mul_f32 v[142:143], v[142:143], s[2:3] op_sel_hi:[1,0]
	v_cvt_pk_bf16_f32 v140, v140, v141
	v_pk_fma_f32 v[136:137], v[100:101], v[152:153], v[136:137] neg_lo:[1,0,0] neg_hi:[1,0,0]
	v_pk_fma_f32 v[136:137], v[136:137], v[154:155], v[96:97]
	v_pk_mul_f32 v[136:137], v[136:137], s[2:3] op_sel_hi:[1,0]
	v_cvt_pk_bf16_f32 v141, v142, v143
	v_pk_fma_f32 v[138:139], v[102:103], v[152:153], v[138:139]
	v_pk_fma_f32 v[138:139], v[138:139], v[154:155], v[98:99]
	v_pk_mul_f32 v[138:139], v[138:139], s[2:3] op_sel_hi:[1,0]
	v_cvt_pk_bf16_f32 v142, v136, v137
	v_cvt_pk_bf16_f32 v143, v138, v139
	global_store_dwordx4 v[156:157], v[140:143], off

.LBB0_389:
	s_or_b64 exec, exec, s[0:1]
	s_waitcnt lgkmcnt(0)
	v_mov_b32_e32 v138, v174
	v_mov_b32_e32 v140, v175
	ds_bpermute_b32 v176, v234, v222 offset:192
	ds_bpermute_b32 v177, v234, v223 offset:192
	v_add_u32_e32 v136, 48, v200
	v_ashrrev_i32_e32 v137, 31, v136
	v_lshlrev_b64 v[110:111], 11, v[110:111]
	v_lshl_add_u64 v[110:111], s[24:25], 0, v[110:111]
	v_lshl_add_u64 v[110:111], v[196:197], 1, v[110:111]
	v_mov_b32_e32 v139, v138
	v_mov_b32_e32 v141, v140
	s_and_saveexec_b64 s[0:1], vcc
	s_cbranch_execz .LBB0_391
	v_pk_fma_f32 v[124:125], v[108:109], v[138:139], v[124:125] neg_lo:[1,0,0] neg_hi:[1,0,0]
	s_mov_b32 s2, 0x3d800000
	v_pk_fma_f32 v[124:125], v[124:125], v[140:141], v[104:105]
	v_pk_mul_f32 v[124:125], v[124:125], s[2:3] op_sel_hi:[1,0]
	v_pk_fma_f32 v[126:127], v[198:199], v[138:139], v[126:127]
	v_pk_fma_f32 v[126:127], v[126:127], v[140:141], v[106:107]
	v_pk_mul_f32 v[126:127], v[126:127], s[2:3] op_sel_hi:[1,0]
	v_cvt_pk_bf16_f32 v124, v124, v125
	v_pk_fma_f32 v[120:121], v[100:101], v[138:139], v[120:121] neg_lo:[1,0,0] neg_hi:[1,0,0]
	v_pk_fma_f32 v[120:121], v[120:121], v[140:141], v[96:97]
	v_pk_mul_f32 v[120:121], v[120:121], s[2:3] op_sel_hi:[1,0]
	v_cvt_pk_bf16_f32 v125, v126, v127
	v_pk_fma_f32 v[122:123], v[102:103], v[138:139], v[122:123]
	v_pk_fma_f32 v[122:123], v[122:123], v[140:141], v[98:99]
	v_pk_mul_f32 v[122:123], v[122:123], s[2:3] op_sel_hi:[1,0]
	v_cvt_pk_bf16_f32 v126, v120, v121
	v_cvt_pk_bf16_f32 v127, v122, v123
	global_store_dwordx4 v[110:111], v[124:127], off

.LBB0_393:
	s_or_b64 exec, exec, s[0:1]
	s_waitcnt lgkmcnt(0)
	v_mov_b32_e32 v120, v176
	v_mov_b32_e32 v122, v177
	ds_bpermute_b32 v174, v234, v213
	ds_bpermute_b32 v175, v234, v241
	v_add_u32_e32 v118, 0x80, v200
	v_ashrrev_i32_e32 v119, 31, v118
	v_lshlrev_b64 v[124:125], 11, v[136:137]
	v_lshl_add_u64 v[124:125], s[24:25], 0, v[124:125]
	v_lshl_add_u64 v[124:125], v[196:197], 1, v[124:125]
	v_mov_b32_e32 v121, v120
	v_mov_b32_e32 v123, v122
	s_and_saveexec_b64 s[0:1], vcc
	s_cbranch_execz .LBB0_395
	v_pk_fma_f32 v[92:93], v[108:109], v[120:121], v[92:93] neg_lo:[1,0,0] neg_hi:[1,0,0]
	s_mov_b32 s2, 0x3d800000
	v_pk_fma_f32 v[92:93], v[92:93], v[122:123], v[104:105]
	v_pk_mul_f32 v[92:93], v[92:93], s[2:3] op_sel_hi:[1,0]
	v_pk_fma_f32 v[94:95], v[198:199], v[120:121], v[94:95]
	v_pk_fma_f32 v[94:95], v[94:95], v[122:123], v[106:107]
	v_pk_mul_f32 v[94:95], v[94:95], s[2:3] op_sel_hi:[1,0]
	v_cvt_pk_bf16_f32 v92, v92, v93
	v_pk_fma_f32 v[80:81], v[100:101], v[120:121], v[80:81] neg_lo:[1,0,0] neg_hi:[1,0,0]
	v_pk_fma_f32 v[80:81], v[80:81], v[122:123], v[96:97]
	v_pk_mul_f32 v[80:81], v[80:81], s[2:3] op_sel_hi:[1,0]
	v_cvt_pk_bf16_f32 v93, v94, v95
	v_pk_fma_f32 v[82:83], v[102:103], v[120:121], v[82:83]
	v_pk_fma_f32 v[82:83], v[82:83], v[122:123], v[98:99]
	v_pk_mul_f32 v[82:83], v[82:83], s[2:3] op_sel_hi:[1,0]
	v_cvt_pk_bf16_f32 v94, v80, v81
	v_cvt_pk_bf16_f32 v95, v82, v83
	global_store_dwordx4 v[124:125], v[92:95], off

.LBB0_397:
	s_or_b64 exec, exec, s[0:1]
	s_waitcnt lgkmcnt(0)
	v_mov_b32_e32 v82, v174
	v_mov_b32_e32 v92, v175
	ds_bpermute_b32 v176, v234, v213 offset:64
	ds_bpermute_b32 v177, v234, v241 offset:64
	v_add_u32_e32 v80, 0x90, v200
	v_ashrrev_i32_e32 v81, 31, v80
	v_lshlrev_b64 v[94:95], 11, v[118:119]
	v_lshl_add_u64 v[94:95], s[24:25], 0, v[94:95]
	v_lshl_add_u64 v[94:95], v[196:197], 1, v[94:95]
	v_mov_b32_e32 v83, v82
	v_mov_b32_e32 v93, v92
	s_and_saveexec_b64 s[0:1], vcc
	s_cbranch_execz .LBB0_399
	v_pk_fma_f32 v[60:61], v[108:109], v[82:83], v[60:61] neg_lo:[1,0,0] neg_hi:[1,0,0]
	s_mov_b32 s2, 0x3d800000
	v_pk_fma_f32 v[60:61], v[60:61], v[92:93], v[104:105]
	v_pk_mul_f32 v[60:61], v[60:61], s[2:3] op_sel_hi:[1,0]
	v_pk_fma_f32 v[62:63], v[198:199], v[82:83], v[62:63]
	v_pk_fma_f32 v[62:63], v[62:63], v[92:93], v[106:107]
	v_pk_mul_f32 v[62:63], v[62:63], s[2:3] op_sel_hi:[1,0]
	v_cvt_pk_bf16_f32 v60, v60, v61
	v_pk_fma_f32 v[56:57], v[100:101], v[82:83], v[56:57] neg_lo:[1,0,0] neg_hi:[1,0,0]
	v_pk_fma_f32 v[56:57], v[56:57], v[92:93], v[96:97]
	v_pk_mul_f32 v[56:57], v[56:57], s[2:3] op_sel_hi:[1,0]
	v_cvt_pk_bf16_f32 v61, v62, v63
	v_pk_fma_f32 v[58:59], v[102:103], v[82:83], v[58:59]
	v_pk_fma_f32 v[58:59], v[58:59], v[92:93], v[98:99]
	v_pk_mul_f32 v[58:59], v[58:59], s[2:3] op_sel_hi:[1,0]
	v_cvt_pk_bf16_f32 v62, v56, v57
	v_cvt_pk_bf16_f32 v63, v58, v59
	global_store_dwordx4 v[94:95], v[60:63], off

.LBB0_401:
	s_or_b64 exec, exec, s[0:1]
	s_waitcnt lgkmcnt(0)
	v_mov_b32_e32 v58, v176
	v_mov_b32_e32 v60, v177
	ds_bpermute_b32 v174, v234, v213 offset:128
	ds_bpermute_b32 v175, v234, v241 offset:128
	v_add_u32_e32 v56, 0xa0, v200
	v_ashrrev_i32_e32 v57, 31, v56
	v_lshlrev_b64 v[62:63], 11, v[80:81]
	v_lshl_add_u64 v[62:63], s[24:25], 0, v[62:63]
	v_lshl_add_u64 v[62:63], v[196:197], 1, v[62:63]
	v_mov_b32_e32 v59, v58
	v_mov_b32_e32 v61, v60
	s_and_saveexec_b64 s[0:1], vcc
	s_cbranch_execz .LBB0_403
	v_pk_fma_f32 v[44:45], v[108:109], v[58:59], v[44:45] neg_lo:[1,0,0] neg_hi:[1,0,0]
	s_mov_b32 s2, 0x3d800000
	v_pk_fma_f32 v[44:45], v[44:45], v[60:61], v[104:105]
	v_pk_mul_f32 v[44:45], v[44:45], s[2:3] op_sel_hi:[1,0]
	v_pk_fma_f32 v[46:47], v[198:199], v[58:59], v[46:47]
	v_pk_fma_f32 v[46:47], v[46:47], v[60:61], v[106:107]
	v_pk_mul_f32 v[46:47], v[46:47], s[2:3] op_sel_hi:[1,0]
	v_cvt_pk_bf16_f32 v44, v44, v45
	v_pk_fma_f32 v[40:41], v[100:101], v[58:59], v[40:41] neg_lo:[1,0,0] neg_hi:[1,0,0]
	v_pk_fma_f32 v[40:41], v[40:41], v[60:61], v[96:97]
	v_pk_mul_f32 v[40:41], v[40:41], s[2:3] op_sel_hi:[1,0]
	v_cvt_pk_bf16_f32 v45, v46, v47
	v_pk_fma_f32 v[42:43], v[102:103], v[58:59], v[42:43]
	v_pk_fma_f32 v[42:43], v[42:43], v[60:61], v[98:99]
	v_pk_mul_f32 v[42:43], v[42:43], s[2:3] op_sel_hi:[1,0]
	v_cvt_pk_bf16_f32 v46, v40, v41
	v_cvt_pk_bf16_f32 v47, v42, v43
	global_store_dwordx4 v[62:63], v[44:47], off

.LBB0_405:
	s_or_b64 exec, exec, s[0:1]
	s_waitcnt lgkmcnt(0)
	v_mov_b32_e32 v40, v174
	v_mov_b32_e32 v42, v175
	ds_bpermute_b32 v176, v234, v213 offset:192
	ds_bpermute_b32 v177, v234, v241 offset:192
	v_add_u32_e32 v44, 0xb0, v200
	v_ashrrev_i32_e32 v45, 31, v44
	v_lshlrev_b64 v[46:47], 11, v[56:57]
	v_lshl_add_u64 v[46:47], s[24:25], 0, v[46:47]
	v_lshl_add_u64 v[46:47], v[196:197], 1, v[46:47]
	v_mov_b32_e32 v41, v40
	v_mov_b32_e32 v43, v42
	s_and_saveexec_b64 s[0:1], vcc
	s_cbranch_execz .LBB0_407
	v_pk_fma_f32 v[28:29], v[108:109], v[40:41], v[28:29] neg_lo:[1,0,0] neg_hi:[1,0,0]
	s_mov_b32 s2, 0x3d800000
	v_pk_fma_f32 v[28:29], v[28:29], v[42:43], v[104:105]
	v_mov_b32_e32 v48, v40
	v_pk_mul_f32 v[28:29], v[28:29], s[2:3] op_sel_hi:[1,0]
	v_mov_b32_e32 v49, v40
	v_pk_fma_f32 v[30:31], v[198:199], v[40:41], v[30:31]
	v_mov_b32_e32 v50, v42
	v_mov_b32_e32 v51, v42
	v_pk_fma_f32 v[30:31], v[30:31], v[42:43], v[106:107]
	v_pk_mul_f32 v[30:31], v[30:31], s[2:3] op_sel_hi:[1,0]
	v_cvt_pk_bf16_f32 v28, v28, v29
	v_pk_fma_f32 v[24:25], v[100:101], v[40:41], v[24:25] neg_lo:[1,0,0] neg_hi:[1,0,0]
	v_pk_fma_f32 v[24:25], v[24:25], v[42:43], v[96:97]
	v_pk_mul_f32 v[24:25], v[24:25], s[2:3] op_sel_hi:[1,0]
	v_cvt_pk_bf16_f32 v29, v30, v31
	v_pk_fma_f32 v[26:27], v[102:103], v[40:41], v[26:27]
	v_pk_fma_f32 v[26:27], v[26:27], v[42:43], v[98:99]
	v_pk_mul_f32 v[26:27], v[26:27], s[2:3] op_sel_hi:[1,0]
	v_cvt_pk_bf16_f32 v30, v24, v25
	v_cvt_pk_bf16_f32 v31, v26, v27
	global_store_dwordx4 v[46:47], v[28:31], off

.LBB0_409:
	s_or_b64 exec, exec, s[0:1]
	s_waitcnt lgkmcnt(0)
	v_mov_b32_e32 v18, v176
	v_mov_b32_e32 v20, v177
	v_mov_b32_e32 v19, v18
	v_lshlrev_b64 v[16:17], 11, v[44:45]
	v_lshl_add_u64 v[16:17], s[24:25], 0, v[16:17]
	v_lshl_add_u64 v[16:17], v[196:197], 1, v[16:17]
	v_mov_b32_e32 v21, v20
	s_and_saveexec_b64 s[0:1], vcc
	s_cbranch_execz .LBB0_411
	v_pk_fma_f32 v[12:13], v[108:109], v[18:19], v[12:13] neg_lo:[1,0,0] neg_hi:[1,0,0]
	s_mov_b32 s2, 0x3d800000
	v_pk_fma_f32 v[12:13], v[12:13], v[20:21], v[104:105]
	v_pk_mul_f32 v[12:13], v[12:13], s[2:3] op_sel_hi:[1,0]
	v_pk_fma_f32 v[14:15], v[198:199], v[18:19], v[14:15]
	v_pk_fma_f32 v[14:15], v[14:15], v[20:21], v[106:107]
	v_pk_mul_f32 v[14:15], v[14:15], s[2:3] op_sel_hi:[1,0]
	v_cvt_pk_bf16_f32 v12, v12, v13
	v_pk_fma_f32 v[8:9], v[100:101], v[18:19], v[8:9] neg_lo:[1,0,0] neg_hi:[1,0,0]
	v_pk_fma_f32 v[8:9], v[8:9], v[20:21], v[96:97]
	v_pk_mul_f32 v[8:9], v[8:9], s[2:3] op_sel_hi:[1,0]
	v_cvt_pk_bf16_f32 v13, v14, v15
	v_pk_fma_f32 v[10:11], v[102:103], v[18:19], v[10:11]
	v_pk_fma_f32 v[10:11], v[10:11], v[20:21], v[98:99]
	v_pk_mul_f32 v[10:11], v[10:11], s[2:3] op_sel_hi:[1,0]
	v_cvt_pk_bf16_f32 v14, v8, v9
	v_cvt_pk_bf16_f32 v15, v10, v11
	global_store_dwordx4 v[16:17], v[12:15], off

.LBB0_856:
	s_lshl_b32 s1, s2, 8
	s_lshl_b32 s0, s0, 8
	v_mov_b32_e32 v160, v179
	v_mov_b32_e32 v80, v210
	s_add_i32 s1, s1, s64
	s_or_b32 s0, s0, s65
	v_readlane_b32 s20, v254, 49
	v_lshl_add_u32 v196, v80, 3, s0
	v_add_u32_e32 v200, s1, v160
	v_ashrrev_i32_e32 v197, 31, v196
	v_ashrrev_i32_e32 v201, 31, v200
	v_lshlrev_b64 v[80:81], 2, v[196:197]
	v_readlane_b32 s21, v254, 50
	v_lshl_add_u64 v[82:83], s[44:45], 0, v[80:81]
	v_lshl_add_u64 v[88:89], s[46:47], 0, v[80:81]
	global_load_dwordx4 v[100:103], v[82:83], off offset:16
	global_load_dwordx4 v[108:111], v[82:83], off
	global_load_dwordx4 v[96:99], v[88:89], off offset:16
	global_load_dwordx4 v[104:107], v[88:89], off
	global_load_dwordx4 v[84:87], v[82:83], off offset:528
	global_load_dwordx4 v[92:95], v[82:83], off offset:512
	s_nop 0
	global_load_dwordx4 v[80:83], v[88:89], off offset:528
	s_nop 0
	global_load_dwordx4 v[88:91], v[88:89], off offset:512
	s_nop 0
	v_lshl_add_u32 v170, v210, 4, v200
	v_lshlrev_b32_e32 v170, 5, v170
	v_add_u32_e32 v232, 0x1000, v170
	global_load_dwordx4 v[160:163], v170, s[20:21] offset:16
	global_load_dwordx4 v[164:167], v170, s[20:21]
	global_load_dwordx4 v[214:217], v232, s[20:21] offset:16
	global_load_dwordx4 v[218:221], v232, s[20:21]
	v_lshlrev_b32_e32 v234, 2, v179
	s_mov_b32 s0, 0x3a800000
	s_mov_b32 s1, 0x800000
	v_add_u32_e32 v202, 16, v200
	v_ashrrev_i32_e32 v203, 31, v202
	v_mov_b64_e32 v[198:199], s[24:25]
	s_waitcnt vmcnt(0)
	v_pk_add_f32 v[160:161], v[160:161], v[162:163]
	v_pk_add_f32 v[164:165], v[164:165], v[166:167]
	v_pk_add_f32 v[160:161], v[164:165], v[160:161]
	v_pk_mul_f32 v[160:161], v[160:161], s[0:1] op_sel_hi:[1,0]
	s_nop 0
	v_fma_f32 v164, -v160, v160, v161
	v_max_f32_e32 v164, 0, v164
	v_add_f32_e32 v164, 0x3727c5ac, v164
	v_cmp_gt_f32_e32 vcc, s1, v164
	v_mul_f32_e32 v165, 0x4b800000, v164
	v_mov_b32_e32 v222, v160
	v_cndmask_b32_e32 v164, v164, v165, vcc
	v_rsq_f32_e32 v164, v164
	s_nop 0
	v_mul_f32_e32 v165, 0x45800000, v164
	v_cndmask_b32_e32 v223, v164, v165, vcc
	v_pk_add_f32 v[214:215], v[214:215], v[216:217]
	v_pk_add_f32 v[218:219], v[218:219], v[220:221]
	v_pk_add_f32 v[214:215], v[218:219], v[214:215]
	v_pk_mul_f32 v[214:215], v[214:215], s[0:1] op_sel_hi:[1,0]
	s_nop 0
	v_fma_f32 v218, -v214, v214, v215
	v_max_f32_e32 v218, 0, v218
	v_add_f32_e32 v218, 0x3727c5ac, v218
	v_cmp_gt_f32_e32 vcc, s1, v218
	v_mul_f32_e32 v219, 0x4b800000, v218
	v_mov_b32_e32 v213, v214
	v_cndmask_b32_e32 v218, v218, v219, vcc
	v_rsq_f32_e32 v218, v218
	s_nop 0
	v_mul_f32_e32 v219, 0x45800000, v218
	v_cndmask_b32_e32 v241, v218, v219, vcc
	ds_bpermute_b32 v174, v234, v222
	ds_bpermute_b32 v175, v234, v223
	ds_bpermute_b32 v176, v234, v222 offset:64
	ds_bpermute_b32 v177, v234, v223 offset:64
	v_xor_b32_e32 v103, 0x80000000, v103
	v_xor_b32_e32 v102, 0x80000000, v102
	v_mad_i64_i32 v[198:199], s[0:1], v200, s78, v[198:199]
	v_lshl_add_u64 v[208:209], v[196:197], 1, v[198:199]
	v_xor_b32_e32 v199, 0x80000000, v111
	v_xor_b32_e32 v198, 0x80000000, v110
	s_waitcnt lgkmcnt(2)
	v_mov_b32_e32 v204, v174
	v_mov_b32_e32 v206, v175
	v_mov_b32_e32 v205, v204
	v_mov_b32_e32 v207, v206
	v_cmp_gt_i32_e32 vcc, s79, v196
	s_and_saveexec_b64 s[0:1], vcc
	s_cbranch_execz .LBB0_858
	v_pk_fma_f32 v[156:157], v[108:109], v[204:205], v[156:157] neg_lo:[1,0,0] neg_hi:[1,0,0]
	v_pk_fma_f32 v[156:157], v[156:157], v[206:207], v[104:105]
	v_pk_fma_f32 v[158:159], v[198:199], v[204:205], v[158:159]
	v_pk_fma_f32 v[152:153], v[100:101], v[204:205], v[152:153] neg_lo:[1,0,0] neg_hi:[1,0,0]
	v_pk_fma_f32 v[158:159], v[158:159], v[206:207], v[106:107]
	v_pk_fma_f32 v[152:153], v[152:153], v[206:207], v[96:97]
	v_cvt_pk_bf16_f32 v156, v156, v157
	v_pk_fma_f32 v[110:111], v[102:103], v[204:205], v[154:155]
	v_pk_fma_f32 v[110:111], v[110:111], v[206:207], v[98:99]
	v_cvt_pk_bf16_f32 v157, v158, v159
	v_cvt_pk_bf16_f32 v158, v152, v153
	v_cvt_pk_bf16_f32 v159, v110, v111
	global_store_dwordx4 v[208:209], v[156:159], off

.LBB0_860:
	s_or_b64 exec, exec, s[0:1]
	s_waitcnt lgkmcnt(0)
	v_mov_b32_e32 v152, v176
	v_mov_b32_e32 v154, v177
	ds_bpermute_b32 v174, v234, v222 offset:128
	ds_bpermute_b32 v175, v234, v223 offset:128
	v_mov_b64_e32 v[156:157], s[24:25]
	v_mov_b32_e32 v153, v152
	v_add_u32_e32 v110, 32, v200
	v_ashrrev_i32_e32 v111, 31, v110
	v_mov_b32_e32 v155, v154
	v_mad_i64_i32 v[156:157], s[0:1], v202, s78, v[156:157]
	v_lshl_add_u64 v[156:157], v[196:197], 1, v[156:157]
	s_and_saveexec_b64 s[0:1], vcc
	s_cbranch_execz .LBB0_862
	v_pk_fma_f32 v[140:141], v[108:109], v[152:153], v[140:141] neg_lo:[1,0,0] neg_hi:[1,0,0]
	v_pk_fma_f32 v[140:141], v[140:141], v[154:155], v[104:105]
	v_cvt_pk_bf16_f32 v140, v140, v141
	v_pk_fma_f32 v[142:143], v[198:199], v[152:153], v[142:143]
	v_pk_fma_f32 v[142:143], v[142:143], v[154:155], v[106:107]
	v_pk_fma_f32 v[136:137], v[100:101], v[152:153], v[136:137] neg_lo:[1,0,0] neg_hi:[1,0,0]
	v_pk_fma_f32 v[136:137], v[136:137], v[154:155], v[96:97]
	v_cvt_pk_bf16_f32 v141, v142, v143
	v_pk_fma_f32 v[138:139], v[102:103], v[152:153], v[138:139]
	v_pk_fma_f32 v[138:139], v[138:139], v[154:155], v[98:99]
	v_cvt_pk_bf16_f32 v142, v136, v137
	v_cvt_pk_bf16_f32 v143, v138, v139
	global_store_dwordx4 v[156:157], v[140:143], off

.LBB0_864:
	s_or_b64 exec, exec, s[0:1]
	s_waitcnt lgkmcnt(0)
	v_mov_b32_e32 v138, v174
	v_mov_b32_e32 v140, v175
	ds_bpermute_b32 v176, v234, v222 offset:192
	ds_bpermute_b32 v177, v234, v223 offset:192
	v_add_u32_e32 v136, 48, v200
	v_ashrrev_i32_e32 v137, 31, v136
	v_mov_b64_e32 v[142:143], s[24:25]
	v_mov_b32_e32 v139, v138
	v_mov_b32_e32 v141, v140
	v_mad_i64_i32 v[110:111], s[0:1], v110, s78, v[142:143]
	v_lshl_add_u64 v[110:111], v[196:197], 1, v[110:111]
	s_and_saveexec_b64 s[0:1], vcc
	s_cbranch_execz .LBB0_866
	v_pk_fma_f32 v[124:125], v[108:109], v[138:139], v[124:125] neg_lo:[1,0,0] neg_hi:[1,0,0]
	v_pk_fma_f32 v[124:125], v[124:125], v[140:141], v[104:105]
	v_pk_fma_f32 v[126:127], v[198:199], v[138:139], v[126:127]
	v_pk_fma_f32 v[126:127], v[126:127], v[140:141], v[106:107]
	v_cvt_pk_bf16_f32 v124, v124, v125
	v_pk_fma_f32 v[120:121], v[100:101], v[138:139], v[120:121] neg_lo:[1,0,0] neg_hi:[1,0,0]
	v_pk_fma_f32 v[120:121], v[120:121], v[140:141], v[96:97]
	v_cvt_pk_bf16_f32 v125, v126, v127
	v_pk_fma_f32 v[122:123], v[102:103], v[138:139], v[122:123]
	v_pk_fma_f32 v[122:123], v[122:123], v[140:141], v[98:99]
	v_cvt_pk_bf16_f32 v126, v120, v121
	v_cvt_pk_bf16_f32 v127, v122, v123
	global_store_dwordx4 v[110:111], v[124:127], off

.LBB0_868:
	s_or_b64 exec, exec, s[0:1]
	s_waitcnt lgkmcnt(0)
	v_mov_b32_e32 v120, v176
	v_mov_b32_e32 v122, v177
	ds_bpermute_b32 v174, v234, v213
	ds_bpermute_b32 v175, v234, v241
	v_add_u32_e32 v118, 0x80, v200
	v_ashrrev_i32_e32 v119, 31, v118
	v_mov_b64_e32 v[124:125], s[24:25]
	v_mov_b32_e32 v121, v120
	v_mov_b32_e32 v123, v122
	v_mad_i64_i32 v[124:125], s[0:1], v136, s78, v[124:125]
	v_lshl_add_u64 v[124:125], v[196:197], 1, v[124:125]
	s_and_saveexec_b64 s[0:1], vcc
	s_cbranch_execz .LBB0_870
	v_pk_fma_f32 v[76:77], v[108:109], v[120:121], v[76:77] neg_lo:[1,0,0] neg_hi:[1,0,0]
	v_pk_fma_f32 v[76:77], v[76:77], v[122:123], v[104:105]
	v_pk_fma_f32 v[78:79], v[198:199], v[120:121], v[78:79]
	v_pk_fma_f32 v[78:79], v[78:79], v[122:123], v[106:107]
	v_cvt_pk_bf16_f32 v76, v76, v77
	v_pk_fma_f32 v[72:73], v[100:101], v[120:121], v[72:73] neg_lo:[1,0,0] neg_hi:[1,0,0]
	v_pk_fma_f32 v[72:73], v[72:73], v[122:123], v[96:97]
	v_cvt_pk_bf16_f32 v77, v78, v79
	v_pk_fma_f32 v[74:75], v[102:103], v[120:121], v[74:75]
	v_pk_fma_f32 v[74:75], v[74:75], v[122:123], v[98:99]
	v_cvt_pk_bf16_f32 v78, v72, v73
	v_cvt_pk_bf16_f32 v79, v74, v75
	global_store_dwordx4 v[124:125], v[76:79], off

.LBB0_872:
	s_or_b64 exec, exec, s[0:1]
	s_waitcnt lgkmcnt(0)
	v_mov_b32_e32 v74, v174
	v_mov_b32_e32 v76, v175
	ds_bpermute_b32 v176, v234, v213 offset:64
	ds_bpermute_b32 v177, v234, v241 offset:64
	v_add_u32_e32 v72, 0x90, v200
	v_ashrrev_i32_e32 v73, 31, v72
	v_mov_b64_e32 v[78:79], s[24:25]
	v_mov_b32_e32 v75, v74
	v_mov_b32_e32 v77, v76
	v_mad_i64_i32 v[78:79], s[0:1], v118, s78, v[78:79]
	v_lshl_add_u64 v[78:79], v[196:197], 1, v[78:79]
	s_and_saveexec_b64 s[0:1], vcc
	s_cbranch_execz .LBB0_874
	v_pk_fma_f32 v[60:61], v[108:109], v[74:75], v[60:61] neg_lo:[1,0,0] neg_hi:[1,0,0]
	v_pk_fma_f32 v[60:61], v[60:61], v[76:77], v[104:105]
	v_pk_fma_f32 v[62:63], v[198:199], v[74:75], v[62:63]
	v_pk_fma_f32 v[62:63], v[62:63], v[76:77], v[106:107]
	v_cvt_pk_bf16_f32 v60, v60, v61
	v_pk_fma_f32 v[56:57], v[100:101], v[74:75], v[56:57] neg_lo:[1,0,0] neg_hi:[1,0,0]
	v_pk_fma_f32 v[56:57], v[56:57], v[76:77], v[96:97]
	v_cvt_pk_bf16_f32 v61, v62, v63
	v_pk_fma_f32 v[58:59], v[102:103], v[74:75], v[58:59]
	v_pk_fma_f32 v[58:59], v[58:59], v[76:77], v[98:99]
	v_cvt_pk_bf16_f32 v62, v56, v57
	v_cvt_pk_bf16_f32 v63, v58, v59
	global_store_dwordx4 v[78:79], v[60:63], off

.LBB0_876:
	s_or_b64 exec, exec, s[0:1]
	s_waitcnt lgkmcnt(0)
	v_mov_b32_e32 v58, v176
	v_mov_b32_e32 v60, v177
	ds_bpermute_b32 v174, v234, v213 offset:128
	ds_bpermute_b32 v175, v234, v241 offset:128
	v_add_u32_e32 v56, 0xa0, v200
	v_ashrrev_i32_e32 v57, 31, v56
	v_mov_b64_e32 v[62:63], s[24:25]
	v_mov_b32_e32 v59, v58
	v_mov_b32_e32 v61, v60
	v_mad_i64_i32 v[62:63], s[0:1], v72, s78, v[62:63]
	v_lshl_add_u64 v[62:63], v[196:197], 1, v[62:63]
	s_and_saveexec_b64 s[0:1], vcc
	s_cbranch_execz .LBB0_878
	v_pk_fma_f32 v[44:45], v[108:109], v[58:59], v[44:45] neg_lo:[1,0,0] neg_hi:[1,0,0]
	v_pk_fma_f32 v[44:45], v[44:45], v[60:61], v[104:105]
	v_pk_fma_f32 v[46:47], v[198:199], v[58:59], v[46:47]
	v_pk_fma_f32 v[46:47], v[46:47], v[60:61], v[106:107]
	v_cvt_pk_bf16_f32 v44, v44, v45
	v_pk_fma_f32 v[40:41], v[100:101], v[58:59], v[40:41] neg_lo:[1,0,0] neg_hi:[1,0,0]
	v_pk_fma_f32 v[40:41], v[40:41], v[60:61], v[96:97]
	v_cvt_pk_bf16_f32 v45, v46, v47
	v_pk_fma_f32 v[42:43], v[102:103], v[58:59], v[42:43]
	v_pk_fma_f32 v[42:43], v[42:43], v[60:61], v[98:99]
	v_cvt_pk_bf16_f32 v46, v40, v41
	v_cvt_pk_bf16_f32 v47, v42, v43
	global_store_dwordx4 v[62:63], v[44:47], off

.LBB0_880:
	s_or_b64 exec, exec, s[0:1]
	s_waitcnt lgkmcnt(0)
	v_mov_b32_e32 v40, v174
	v_mov_b32_e32 v42, v175
	ds_bpermute_b32 v176, v234, v213 offset:192
	ds_bpermute_b32 v177, v234, v241 offset:192
	v_add_u32_e32 v44, 0xb0, v200
	v_ashrrev_i32_e32 v45, 31, v44
	v_mov_b64_e32 v[46:47], s[24:25]
	v_mov_b32_e32 v41, v40
	v_mov_b32_e32 v43, v42
	v_mad_i64_i32 v[46:47], s[0:1], v56, s78, v[46:47]
	v_lshl_add_u64 v[46:47], v[196:197], 1, v[46:47]
	s_and_saveexec_b64 s[0:1], vcc
	s_cbranch_execz .LBB0_882
	v_pk_fma_f32 v[28:29], v[108:109], v[40:41], v[28:29] neg_lo:[1,0,0] neg_hi:[1,0,0]
	v_mov_b32_e32 v48, v40
	v_pk_fma_f32 v[28:29], v[28:29], v[42:43], v[104:105]
	v_mov_b32_e32 v49, v40
	v_pk_fma_f32 v[30:31], v[198:199], v[40:41], v[30:31]
	v_mov_b32_e32 v50, v42
	v_mov_b32_e32 v51, v42
	v_pk_fma_f32 v[30:31], v[30:31], v[42:43], v[106:107]
	v_cvt_pk_bf16_f32 v28, v28, v29
	v_pk_fma_f32 v[24:25], v[100:101], v[40:41], v[24:25] neg_lo:[1,0,0] neg_hi:[1,0,0]
	v_pk_fma_f32 v[24:25], v[24:25], v[42:43], v[96:97]
	v_cvt_pk_bf16_f32 v29, v30, v31
	v_pk_fma_f32 v[26:27], v[102:103], v[40:41], v[26:27]
	v_pk_fma_f32 v[26:27], v[26:27], v[42:43], v[98:99]
	v_cvt_pk_bf16_f32 v30, v24, v25
	v_cvt_pk_bf16_f32 v31, v26, v27
	global_store_dwordx4 v[46:47], v[28:31], off

.LBB0_884:
	s_or_b64 exec, exec, s[0:1]
	s_waitcnt lgkmcnt(0)
	v_mov_b32_e32 v18, v176
	v_mov_b32_e32 v20, v177
	v_mov_b32_e32 v19, v18
	v_mov_b64_e32 v[16:17], s[24:25]
	v_mad_i64_i32 v[16:17], s[0:1], v44, s78, v[16:17]
	v_lshl_add_u64 v[16:17], v[196:197], 1, v[16:17]
	v_mov_b32_e32 v21, v20
	s_and_saveexec_b64 s[0:1], vcc
	s_cbranch_execz .LBB0_886
	v_pk_fma_f32 v[12:13], v[108:109], v[18:19], v[12:13] neg_lo:[1,0,0] neg_hi:[1,0,0]
	v_pk_fma_f32 v[12:13], v[12:13], v[20:21], v[104:105]
	v_pk_fma_f32 v[14:15], v[198:199], v[18:19], v[14:15]
	v_pk_fma_f32 v[14:15], v[14:15], v[20:21], v[106:107]
	v_cvt_pk_bf16_f32 v12, v12, v13
	v_pk_fma_f32 v[8:9], v[100:101], v[18:19], v[8:9] neg_lo:[1,0,0] neg_hi:[1,0,0]
	v_pk_fma_f32 v[8:9], v[8:9], v[20:21], v[96:97]
	v_cvt_pk_bf16_f32 v13, v14, v15
	v_pk_fma_f32 v[10:11], v[102:103], v[18:19], v[10:11]
	v_pk_fma_f32 v[10:11], v[10:11], v[20:21], v[98:99]
	v_cvt_pk_bf16_f32 v14, v8, v9
	v_cvt_pk_bf16_f32 v15, v10, v11
	global_store_dwordx4 v[16:17], v[12:15], off
